# POST phase: sample-row units moved to workgroups without a second unit
# speedup vs baseline: 1.1911x; 1.0025x over previous
; template <int EPI>
; __device__ __forceinline__ void gemm_phase(const Params& p, const u16* __restrict__ A, int lda, const u16* __restrict__ BT, int ldb,
;                            int K, int N, u16* __restrict__ outb, int ldo, int resid_in, int boff) {
;     ...
;   for (int un = bstart; un < units; un += G) {
;     int tl = un, kbeg = 0, KT = KTALL;
;     bool part_unit = false;
;     if (un >= t_full) { const int v = un - t_full; tl = t_full + v / split; KT = KTALL / split; kbeg = (v % split) * KT; part_unit = true; }
;     int mt = tl / NT, nt = tl % NT;
.Lgm_plain_c:
	s_mov_b32 s36, s5
	s_cmp_lg_u32 s30, 5
	s_cbranch_scc1 .Lgm_plain2_c
	s_cmp_lt_u32 s5, 244
	s_cbranch_scc1 .Lgm_plain2_c
	s_add_u32 s36, s5, 140
	s_cmp_lt_u32 s5, 256
	s_cbranch_scc1 .Lgm_plain2_c
	s_mov_b32 s36, s5
	s_cmp_lt_u32 s5, 384
	s_cbranch_scc1 .Lgm_plain2_c
	s_sub_u32 s36, s5, 140
.Lgm_plain2_c:
	s_mul_hi_u32 s6, s36, s26
	s_mul_i32 s7, s6, s25
	s_sub_u32 s7, s36, s7
	s_branch .Lgm_dec_done_c
